# log-forget cumulative sum: wave-wide scan with DPP row_shr/row_bcast adds and a v_readlane carry instead of seven ds_bpermute round trips per 64 rows
# baseline (speedup 1.0000x reference)
; __device__ __forceinline__ float ld_agent(const float* p) { return __hip_atomic_load(p, __ATOMIC_RELAXED, __HIP_MEMORY_SCOPE_AGENT); }
; __global__ void __launch_bounds__(512, 2) fox_fwd(Args args) {
;     ...
;             for (int ch = 0; ch < SEQ / 64; ++ch) { float v = lf[(size_t)(ch * 64 + lane) * NH];
;                 qmax = fmaxf(qmax, ld_agent(nq + (size_t)(ch * 64 + lane) * NH)); kmax = fmaxf(kmax, ld_agent(nk + (size_t)(ch * 64 + lane) * NH));
; #pragma unroll
;                 for (int o = 1; o < 64; o <<= 1) { const float t = __shfl_up(v, o); if (lane >= o) v += t; }
;                 v += carry; carry = __shfl(v, 63); c[ch * 64 + lane] = v;
;                 if ((ch & 3) == 3) {
; #pragma unroll
;                     for (int o = 1; o < 64; o <<= 1) qmax = fmaxf(qmax, __shfl_xor(qmax, o));
;                     if (lane == 0) QN[ch >> 2] = qmax; qmax = 0.f; } }
.LBB0_871:
	s_waitcnt vmcnt(1)
	v_mov_b32_e32 v26, v30
	v_mov_b32_e32 v33, v31
	v_mov_b32_e32 v34, v32
	s_add_u32 s36, s30, 0x800
	s_addc_u32 s37, s31, 0
	s_waitcnt lgkmcnt(0)
	v_lshl_add_u64 v[22:23], v[4:5], 0, s[36:37]
	global_load_dword v30, v[22:23], off
	v_lshl_add_u64 v[22:23], v[6:7], 0, s[36:37]
	v_add_co_u32_e32 v24, vcc, 0x34c00000, v22
	v_max_f32_e32 v21, v21, v21
	s_nop 0
	v_addc_co_u32_e32 v25, vcc, 0, v23, vcc
	global_load_dword v31, v[24:25], off sc1
	v_add_co_u32_e32 v22, vcc, 0x34e00000, v22
	s_and_b32 s0, s27, 3
	s_nop 0
	v_addc_co_u32_e32 v23, vcc, 0, v23, vcc
	global_load_dword v32, v[22:23], off sc1
	s_cmp_lg_u32 s0, 3
	v_mov_b32_e32 v23, v26
	v_max_f32_e32 v33, v33, v33
	v_max_f32_e32 v21, v21, v33
	v_add_f32_dpp v23, v23, v23 row_shr:1 row_mask:0xf bank_mask:0xf bound_ctrl:0
	s_nop 1
	v_add_f32_dpp v23, v23, v23 row_shr:2 row_mask:0xf bank_mask:0xf bound_ctrl:0
	s_nop 1
	v_add_f32_dpp v23, v23, v23 row_shr:4 row_mask:0xf bank_mask:0xf bound_ctrl:0
	s_nop 1
	v_add_f32_dpp v23, v23, v23 row_shr:8 row_mask:0xf bank_mask:0xf bound_ctrl:0
	s_nop 1
	v_add_f32_dpp v23, v23, v23 row_bcast:15 row_mask:0xa bank_mask:0xf
	s_nop 1
	v_add_f32_dpp v23, v23, v23 row_bcast:31 row_mask:0xc bank_mask:0xf
	s_nop 1
	v_add_f32_e32 v23, v1, v23
	s_nop 1
	v_readlane_b32 s98, v23, 63
	global_store_dword v[2:3], v23, off
	s_nop 1
	v_mov_b32_e32 v1, s98
	s_cbranch_scc1 .LBB0_870
	ds_bpermute_b32 v23, v15, v21
	v_max_f32_e32 v21, v21, v21
	s_waitcnt lgkmcnt(0)
	v_max_f32_e32 v23, v23, v23
	v_max_f32_e32 v21, v21, v23
	ds_bpermute_b32 v23, v16, v21
	s_waitcnt lgkmcnt(0)
	v_max_f32_e32 v23, v23, v23
	v_max_f32_e32 v21, v21, v23
	ds_bpermute_b32 v23, v17, v21
	s_waitcnt lgkmcnt(0)
	v_max_f32_e32 v23, v23, v23
	v_max_f32_e32 v21, v21, v23
	ds_bpermute_b32 v23, v18, v21
	s_waitcnt lgkmcnt(0)
	v_max_f32_e32 v23, v23, v23
	v_max_f32_e32 v21, v21, v23
	ds_bpermute_b32 v23, v19, v21
	s_waitcnt lgkmcnt(0)
	v_max_f32_e32 v23, v23, v23
	v_max_f32_e32 v21, v21, v23
	ds_bpermute_b32 v23, v20, v21
	s_and_saveexec_b64 s[36:37], s[4:5]
	s_cbranch_execz .LBB0_869
	s_waitcnt lgkmcnt(0)
	v_max_f32_e32 v23, v23, v23
	v_max_f32_e32 v21, v21, v21
	s_and_b32 s0, s27, -4
	v_max_f32_e32 v21, v21, v23
	v_mov_b32_e32 v23, s0
	global_store_dword v23, v21, s[28:29]
	s_branch .LBB0_869
